# final candidate: scan v2b + NSA sel LDS-read hoist + top-k scalar compare + GU epilogue row-scale LDS cache with explicit tag init at kernel start
# speedup vs baseline: 1.0186x; 1.0036x over previous
; #define LAS __attribute__((address_space(3)))
; __device__ __forceinline__ unsigned xb_add(unsigned* p, unsigned v) { return __hip_atomic_fetch_add(p, v, __ATOMIC_RELAXED, __HIP_MEMORY_SCOPE_AGENT); }
; __device__ __forceinline__ unsigned xb_xcc_id() { return (unsigned)__builtin_amdgcn_s_getreg((3 << 11) | 20) & 0xFu; }
; __device__ __forceinline__ XcdBarrier xcd_barrier_post(unsigned* bar, volatile LAS unsigned* st) {
;     XcdBarrier b; b.bar = bar; b.x = xb_xcc_id(); b.st = st;
;     if (threadIdx.x == 0) (void)xb_add(&bar[XB_XCNT(b.x)], 1u);
;     return b;
; __global__ void __launch_bounds__(512) mk_fwd(Args a) {
;     extern __shared__ __attribute__((aligned(16))) unsigned char lds_raw[];
;     LAS unsigned char* lds = (LAS unsigned char*)lds_raw;
;     ...
;     unsigned char* ws = a.ws;
;     bf16_t* XB = (bf16_t*)(ws + WS_XB); bf16_t* H = (bf16_t*)(ws + WS_H); bf16_t* P = (bf16_t*)(ws + WS_P); bf16_t* Y = (bf16_t*)(ws + WS_Y); float* SSQ = (float*)(ws + WS_SSQ);
;     volatile LAS unsigned* bst = (volatile LAS unsigned*)(lds + 147392);
;     if (threadIdx.x < 2) bst[threadIdx.x] = 0u;
;     __syncthreads();
;     ...
;     XcdBarrier xbar = xcd_barrier_post((unsigned*)(a.ws + WS_BAR), bst);
_Z6mk_fwd4Args:
	s_load_dwordx2 s[72:73], s[0:1], 0x110
	v_and_b32_e32 v228, 0x3ff, v0
	v_writelane_b32 v252, s2, 0
	s_mov_b64 s[16:17], s[0:1]
	v_cmp_gt_u32_e32 vcc, 2, v228
	s_and_saveexec_b64 s[2:3], vcc
	v_lshl_add_u32 v1, v228, 2, 0
	v_add_u32_e32 v3, 0x20400, v1
	v_add_u32_e32 v1, 0x23fc0, v1
	v_mov_b32_e32 v2, 0
	ds_write_b32 v1, v2
	ds_write_b32 v3, v2
	s_or_b64 exec, exec, s[2:3]
	s_waitcnt lgkmcnt(0)
	s_barrier
	s_add_u32 s2, s72, 0x8000
	s_getreg_b32 s4, hwreg(HW_REG_XCC_ID, 0, 4)
	s_addc_u32 s3, s73, 0
	s_and_b32 s12, s4, 15
	v_cmp_eq_u32_e64 s[6:7], 0, v228
	s_mov_b64 s[4:5], exec
	s_nop 0
	v_writelane_b32 v252, s6, 1
	s_nop 1
	v_writelane_b32 v252, s7, 2
	s_and_b64 s[6:7], s[4:5], s[6:7]
	s_mov_b64 exec, s[6:7]
	s_cbranch_execz .LBB0_5
	s_mov_b64 s[6:7], exec
	v_mbcnt_lo_u32_b32 v1, s6, 0
	v_mbcnt_hi_u32_b32 v1, s7, v1
	v_cmp_eq_u32_e32 vcc, 0, v1
	s_and_b64 s[8:9], exec, vcc
	s_mov_b64 exec, s[8:9]
	s_cbranch_execz .LBB0_5
	s_lshl_b32 s8, s12, 8
	s_bcnt1_i32_b64 s6, s[6:7]
	v_mov_b32_e32 v1, s8
	v_mov_b32_e32 v2, s6
	global_atomic_add v1, v2, s[2:3] offset:1024
